# peeled first K-iteration of each GEMM unit (C=0 on first MFMA per accumulator) replaces the 128 v_mov accumulator zeroing; plus the phase-0 nt loads
# baseline (speedup 1.0000x reference)
; #define PG8_STAGE(bufoff, gbase, voff) do { _Pragma("unroll") for (int _i = 0; _i < 2; ++_i) \
;         __builtin_amdgcn_global_load_lds((const unsigned*)((const char*)(gbase) + (voff)[_i]), (LAS unsigned*)(lds + (bufoff) + ldsw + _i * 8192), 16, 0, 0); } while (0)
; #define PG8_LDA(dst, b, h) do { _Pragma("unroll") for (int m = 0; m < 4; ++m) _Pragma("unroll") for (int k = 0; k < 2; ++k) dst[m][k] = *(const LAS bf16x8*)(lds + PG8_SA(b, h) + aoff + m * 2048 + k * 1024); } while (0)
; #define PG8_LDB(dst, b, h) do { _Pragma("unroll") for (int n = 0; n < 2; ++n) _Pragma("unroll") for (int k = 0; k < 2; ++k) dst[n][k] = *(const LAS bf16x8*)(lds + PG8_SB(b, h) + boff + n * 2048 + k * 1024); } while (0)
; #define PG8_MMA(ai, bj, At, Bt) do { __builtin_amdgcn_s_setprio(1); _Pragma("unroll") for (int m = 0; m < 4; ++m) _Pragma("unroll") for (int n = 0; n < 2; ++n) _Pragma("unroll") for (int k = 0; k < 2; ++k) \
;         acc[ai][bj][m][n] = __builtin_amdgcn_mfma_f32_16x16x32_bf16(Bt[n][k], At[m][k], acc[ai][bj][m][n], 0, 0, 0); __builtin_amdgcn_s_setprio(0); } while (0)
; #define PG8_WAIT_V(n) asm volatile("s_waitcnt vmcnt(" #n ")" ::: "memory")
; #define PG8_WAIT_L(n) asm volatile("s_waitcnt lgkmcnt(" #n ")" ::: "memory")
; #define PG8_BAR __builtin_amdgcn_s_barrier()
; #define PG8_SCHED __builtin_amdgcn_sched_barrier(0)
; __device__ __forceinline__ void gemm_phase(LAS unsigned char* lds, const GP p, const int tid) {
;     ...
;             PG8_LDB(B0, 0, 0); PG8_LDB(B1, 0, 1); PG8_SCHED; PG8_LDA(At, 0, 0); PG8_STAGE(PG8_SA(1, 1), a1 + hstep, voffA);
;             PG8_WAIT_V(8); PG8_WAIT_L(0); PG8_BAR; PG8_MMA(0, 0, At, B0); PG8_MMA(0, 1, At, B1); PG8_BAR; PG8_SCHED;
;             PG8_LDA(At, 0, 1); PG8_STAGE(PG8_SB(0, 0), b2, voffB); PG8_STAGE(PG8_SB(0, 1), b2 + hstep, voffB); PG8_STAGE(PG8_SA(0, 0), a2, voffA);
;             PG8_WAIT_V(8); PG8_WAIT_L(0); PG8_BAR; PG8_MMA(1, 0, At, B0); PG8_MMA(1, 1, At, B1); PG8_BAR; PG8_SCHED;
;     ...
; #pragma unroll
;         for (int a = 0; a < 2; ++a)
; #pragma unroll
;             for (int b = 0; b < 2; ++b)
; #pragma unroll
;                 for (int m = 0; m < 4; ++m)
; #pragma unroll
;                     for (int n = 0; n < 2; ++n) acc[a][b][m][n] = (f32x4){0.f, 0.f, 0.f, 0.f};
;         cur = nxt; cA = nA; cB = nB; ++ui;
;         if (wr == 1) PG8_BAR;
.LBB0_103:
	s_lshl_b32 s42, s80, 8
	s_ashr_i32 s43, s42, 31
	s_add_u32 s82, s82, 0x80
	s_addc_u32 s83, s83, 0
	s_add_u32 s81, s84, 0x100
	s_addc_u32 s91, s85, 0
	s_mov_b32 s98, 0
	v_lshl_add_u64 v[128:129], s[42:43], 2, v[154:155]
	s_branch .LBB0_105
.Lpeel_body:
	s_add_i32 s98, s98, 2
	s_add_u32 s43, s82, 0x80
	s_addc_u32 s99, s83, 0
	s_and_b64 s[86:87], s[84:85], exec
	s_cselect_b32 s87, s77, s99
	s_cselect_b32 s86, s76, s43
	s_add_i32 s43, 0, 0x10000
	s_and_b64 s[84:85], s[84:85], exec
	v_add_u32_e32 v142, s43, v165
	s_cselect_b32 s85, s79, s91
	s_cselect_b32 s84, s78, s81
	s_add_i32 s99, 0, 0x14000
	ds_read_b128 v[130:133], v142
	ds_read_b128 v[134:137], v142 offset:1024
	ds_read_b128 v[138:141], v142 offset:2048
	ds_read_b128 v[180:183], v142 offset:3072
	v_add_u32_e32 v142, s99, v165
	ds_read_b128 v[184:187], v142
	ds_read_b128 v[188:191], v142 offset:1024
	ds_read_b128 v[192:195], v142 offset:2048
	ds_read_b128 v[196:199], v142 offset:3072
	v_lshl_add_u64 v[142:143], s[82:83], 0, v[160:161]
	s_add_i32 m0, s53, 0xc000
	ds_read_b128 v[200:203], v167
	ds_read_b128 v[204:207], v167 offset:1024
	ds_read_b128 v[208:211], v167 offset:2048
	ds_read_b128 v[218:221], v167 offset:3072
	ds_read_b128 v[222:225], v167 offset:4096
	ds_read_b128 v[226:229], v167 offset:5120
	ds_read_b128 v[230:233], v167 offset:6144
	ds_read_b128 v[234:237], v167 offset:7168
	global_load_lds_dwordx4 v[142:143], off
	v_lshl_add_u64 v[142:143], s[82:83], 0, v[162:163]
	s_add_i32 m0, s53, 0xe000
	s_nop 0
	global_load_lds_dwordx4 v[142:143], off
	s_waitcnt vmcnt(8)
	s_waitcnt lgkmcnt(0)
	s_barrier
	s_setprio 1
	s_waitcnt lgkmcnt(0)
	v_mfma_f32_16x16x32_bf16 v[124:127], v[130:133], v[200:203], 0
	v_mfma_f32_16x16x32_bf16 v[120:123], v[138:141], v[200:203], 0
	v_mfma_f32_16x16x32_bf16 v[108:111], v[130:133], v[208:211], 0
	v_mfma_f32_16x16x32_bf16 v[104:107], v[138:141], v[208:211], 0
	v_mfma_f32_16x16x32_bf16 v[92:95], v[130:133], v[222:225], 0
	v_mfma_f32_16x16x32_bf16 v[88:91], v[138:141], v[222:225], 0
	v_mfma_f32_16x16x32_bf16 v[76:79], v[130:133], v[230:233], 0
	v_mfma_f32_16x16x32_bf16 v[72:75], v[138:141], v[230:233], 0
	v_mfma_f32_16x16x32_bf16 v[124:127], v[134:137], v[204:207], v[124:127]
	v_mfma_f32_16x16x32_bf16 v[120:123], v[180:183], v[204:207], v[120:123]
	v_mfma_f32_16x16x32_bf16 v[108:111], v[134:137], v[218:221], v[108:111]
	v_mfma_f32_16x16x32_bf16 v[104:107], v[180:183], v[218:221], v[104:107]
	v_mfma_f32_16x16x32_bf16 v[92:95], v[134:137], v[226:229], v[92:95]
	v_mfma_f32_16x16x32_bf16 v[88:91], v[180:183], v[226:229], v[88:91]
	v_mfma_f32_16x16x32_bf16 v[76:79], v[134:137], v[234:237], v[76:79]
	v_mfma_f32_16x16x32_bf16 v[72:75], v[180:183], v[234:237], v[72:75]
	s_setprio 0
	s_setprio 1
	v_mfma_f32_16x16x32_bf16 v[116:119], v[184:187], v[200:203], 0
	v_mfma_f32_16x16x32_bf16 v[112:115], v[192:195], v[200:203], 0
	v_mfma_f32_16x16x32_bf16 v[100:103], v[184:187], v[208:211], 0
	v_mfma_f32_16x16x32_bf16 v[96:99], v[192:195], v[208:211], 0
	v_mfma_f32_16x16x32_bf16 v[84:87], v[184:187], v[222:225], 0
	v_mfma_f32_16x16x32_bf16 v[80:83], v[192:195], v[222:225], 0
	v_mfma_f32_16x16x32_bf16 v[68:71], v[184:187], v[230:233], 0
	v_mfma_f32_16x16x32_bf16 v[64:67], v[192:195], v[230:233], 0
	v_mfma_f32_16x16x32_bf16 v[116:119], v[188:191], v[204:207], v[116:119]
	v_mfma_f32_16x16x32_bf16 v[112:115], v[196:199], v[204:207], v[112:115]
	v_mfma_f32_16x16x32_bf16 v[100:103], v[188:191], v[218:221], v[100:103]
	v_mfma_f32_16x16x32_bf16 v[96:99], v[196:199], v[218:221], v[96:99]
	v_mfma_f32_16x16x32_bf16 v[84:87], v[188:191], v[226:229], v[84:87]
	v_mfma_f32_16x16x32_bf16 v[80:83], v[196:199], v[226:229], v[80:83]
	v_mfma_f32_16x16x32_bf16 v[68:71], v[188:191], v[234:237], v[68:71]
	v_mfma_f32_16x16x32_bf16 v[64:67], v[196:199], v[234:237], v[64:67]
	s_setprio 0
	s_barrier
	s_add_i32 s43, s43, s52
	v_lshl_add_u64 v[142:143], s[84:85], 0, v[148:149]
	s_mov_b32 m0, s43
	ds_read_b128 v[200:203], v167 offset:16384
	ds_read_b128 v[204:207], v167 offset:17408
	ds_read_b128 v[208:211], v167 offset:18432
	ds_read_b128 v[218:221], v167 offset:19456
	ds_read_b128 v[222:225], v167 offset:20480
	ds_read_b128 v[226:229], v167 offset:21504
	ds_read_b128 v[230:233], v167 offset:22528
	ds_read_b128 v[234:237], v167 offset:23552
	global_load_lds_dwordx4 v[142:143], off
	s_add_i32 m0, s43, 0x2000
	v_lshl_add_u64 v[238:239], s[84:85], 0, v[152:153]
	s_add_u32 s84, s84, s74
	s_addc_u32 s85, s85, 0
	s_add_i32 s43, s99, s52
	global_load_lds_dwordx4 v[238:239], off
	v_lshl_add_u64 v[240:241], s[84:85], 0, v[148:149]
	s_mov_b32 m0, s43
	v_lshl_add_u64 v[242:243], s[84:85], 0, v[152:153]
	global_load_lds_dwordx4 v[240:241], off
	s_add_i32 m0, s43, 0x2000
	v_lshl_add_u64 v[244:245], s[86:87], 0, v[146:147]
	global_load_lds_dwordx4 v[242:243], off
	s_mov_b32 m0, s53
	v_lshl_add_u64 v[246:247], s[86:87], 0, v[150:151]
	global_load_lds_dwordx4 v[244:245], off
	s_mov_b32 m0, s54
	s_nop 0
	global_load_lds_dwordx4 v[246:247], off
	s_waitcnt vmcnt(8)
	s_waitcnt lgkmcnt(0)
	s_barrier
; #define PG8_STAGE(bufoff, gbase, voff) do { _Pragma("unroll") for (int _i = 0; _i < 2; ++_i) \
;         __builtin_amdgcn_global_load_lds((const unsigned*)((const char*)(gbase) + (voff)[_i]), (LAS unsigned*)(lds + (bufoff) + ldsw + _i * 8192), 16, 0, 0); } while (0)
; #define PG8_LDA(dst, b, h) do { _Pragma("unroll") for (int m = 0; m < 4; ++m) _Pragma("unroll") for (int k = 0; k < 2; ++k) dst[m][k] = *(const LAS bf16x8*)(lds + PG8_SA(b, h) + aoff + m * 2048 + k * 1024); } while (0)
; #define PG8_LDB(dst, b, h) do { _Pragma("unroll") for (int n = 0; n < 2; ++n) _Pragma("unroll") for (int k = 0; k < 2; ++k) dst[n][k] = *(const LAS bf16x8*)(lds + PG8_SB(b, h) + boff + n * 2048 + k * 1024); } while (0)
; #define PG8_MMA(ai, bj, At, Bt) do { __builtin_amdgcn_s_setprio(1); _Pragma("unroll") for (int m = 0; m < 4; ++m) _Pragma("unroll") for (int n = 0; n < 2; ++n) _Pragma("unroll") for (int k = 0; k < 2; ++k) \
;         acc[ai][bj][m][n] = __builtin_amdgcn_mfma_f32_16x16x32_bf16(Bt[n][k], At[m][k], acc[ai][bj][m][n], 0, 0, 0); __builtin_amdgcn_s_setprio(0); } while (0)
; #define PG8_WAIT_V(n) asm volatile("s_waitcnt vmcnt(" #n ")" ::: "memory")
; #define PG8_WAIT_L(n) asm volatile("s_waitcnt lgkmcnt(" #n ")" ::: "memory")
; #define PG8_BAR __builtin_amdgcn_s_barrier()
; #define PG8_SCHED __builtin_amdgcn_sched_barrier(0)
; __device__ __forceinline__ void gemm_phase(LAS unsigned char* lds, const GP p, const int tid) {
;     ...
;             PG8_WAIT_V(8); PG8_WAIT_L(0); PG8_BAR; PG8_MMA(1, 0, At, B0); PG8_MMA(1, 1, At, B1); PG8_BAR; PG8_SCHED;
;             PG8_LDB(B0, 1, 0); PG8_LDB(B1, 1, 1); PG8_SCHED; PG8_LDA(At, 1, 0); PG8_STAGE(PG8_SA(0, 1), a2 + hstep, voffA);
;             PG8_WAIT_V(8); PG8_WAIT_L(0); PG8_BAR; PG8_MMA(0, 0, At, B0); PG8_MMA(0, 1, At, B1); PG8_BAR; PG8_SCHED;
	s_setprio 1
	s_waitcnt lgkmcnt(0)
	v_mfma_f32_16x16x32_bf16 v[60:63], v[130:133], v[200:203], 0
	v_mfma_f32_16x16x32_bf16 v[56:59], v[138:141], v[200:203], 0
	v_mfma_f32_16x16x32_bf16 v[44:47], v[130:133], v[208:211], 0
	v_mfma_f32_16x16x32_bf16 v[40:43], v[138:141], v[208:211], 0
	v_mfma_f32_16x16x32_bf16 v[28:31], v[130:133], v[222:225], 0
	v_mfma_f32_16x16x32_bf16 v[24:27], v[138:141], v[222:225], 0
	v_mfma_f32_16x16x32_bf16 v[12:15], v[130:133], v[230:233], 0
	v_mfma_f32_16x16x32_bf16 v[8:11], v[138:141], v[230:233], 0
	v_mfma_f32_16x16x32_bf16 v[60:63], v[134:137], v[204:207], v[60:63]
	v_mfma_f32_16x16x32_bf16 v[56:59], v[180:183], v[204:207], v[56:59]
	v_mfma_f32_16x16x32_bf16 v[44:47], v[134:137], v[218:221], v[44:47]
	v_mfma_f32_16x16x32_bf16 v[40:43], v[180:183], v[218:221], v[40:43]
	v_mfma_f32_16x16x32_bf16 v[28:31], v[134:137], v[226:229], v[28:31]
	v_mfma_f32_16x16x32_bf16 v[24:27], v[180:183], v[226:229], v[24:27]
	v_mfma_f32_16x16x32_bf16 v[12:15], v[134:137], v[234:237], v[12:15]
	v_mfma_f32_16x16x32_bf16 v[8:11], v[180:183], v[234:237], v[8:11]
	s_setprio 0
	s_setprio 1
	v_mfma_f32_16x16x32_bf16 v[52:55], v[184:187], v[200:203], 0
	v_mfma_f32_16x16x32_bf16 v[48:51], v[192:195], v[200:203], 0
	v_mfma_f32_16x16x32_bf16 v[36:39], v[184:187], v[208:211], 0
	v_mfma_f32_16x16x32_bf16 v[32:35], v[192:195], v[208:211], 0
	v_mfma_f32_16x16x32_bf16 v[20:23], v[184:187], v[222:225], 0
	v_mfma_f32_16x16x32_bf16 v[16:19], v[192:195], v[222:225], 0
	v_mfma_f32_16x16x32_bf16 v[4:7], v[184:187], v[230:233], 0
	v_mfma_f32_16x16x32_bf16 v[0:3], v[192:195], v[230:233], 0
	v_mfma_f32_16x16x32_bf16 v[52:55], v[188:191], v[204:207], v[52:55]
	v_mfma_f32_16x16x32_bf16 v[48:51], v[196:199], v[204:207], v[48:51]
	v_mfma_f32_16x16x32_bf16 v[36:39], v[188:191], v[218:221], v[36:39]
	v_mfma_f32_16x16x32_bf16 v[32:35], v[196:199], v[218:221], v[32:35]
	v_mfma_f32_16x16x32_bf16 v[20:23], v[188:191], v[226:229], v[20:23]
	v_mfma_f32_16x16x32_bf16 v[16:19], v[196:199], v[226:229], v[16:19]
	v_mfma_f32_16x16x32_bf16 v[4:7], v[188:191], v[234:237], v[4:7]
	v_mfma_f32_16x16x32_bf16 v[0:3], v[196:199], v[234:237], v[0:3]
	s_setprio 0
	s_barrier
	s_add_i32 s43, 0, 0x18000
	v_add_u32_e32 v144, s43, v165
	s_add_i32 s99, 0, 0x1c000
	ds_read_b128 v[130:133], v144
	ds_read_b128 v[134:137], v144 offset:1024
	ds_read_b128 v[138:141], v144 offset:2048
	ds_read_b128 v[180:183], v144 offset:3072
	v_add_u32_e32 v144, s99, v165
	ds_read_b128 v[184:187], v144
	ds_read_b128 v[188:191], v144 offset:1024
	ds_read_b128 v[192:195], v144 offset:2048
	ds_read_b128 v[196:199], v144 offset:3072
	s_add_u32 s84, s86, s74
	s_addc_u32 s85, s87, 0
	s_mov_b32 m0, s55
	v_lshl_add_u64 v[248:249], s[84:85], 0, v[146:147]
	ds_read_b128 v[200:203], v167 offset:32768
	ds_read_b128 v[204:207], v167 offset:33792
	ds_read_b128 v[208:211], v167 offset:34816
	ds_read_b128 v[218:221], v167 offset:35840
	ds_read_b128 v[222:225], v167 offset:36864
	ds_read_b128 v[226:229], v167 offset:37888
	ds_read_b128 v[230:233], v167 offset:38912
	ds_read_b128 v[234:237], v167 offset:39936
	global_load_lds_dwordx4 v[248:249], off
	v_lshl_add_u64 v[248:249], s[84:85], 0, v[150:151]
	s_mov_b32 m0, s56
	s_nop 0
	global_load_lds_dwordx4 v[248:249], off
	s_waitcnt vmcnt(8)
	s_waitcnt lgkmcnt(0)
	s_barrier
	s_setprio 1
	s_waitcnt lgkmcnt(0)
	v_mfma_f32_16x16x32_bf16 v[124:127], v[130:133], v[200:203], v[124:127]
	v_mfma_f32_16x16x32_bf16 v[120:123], v[138:141], v[200:203], v[120:123]
	v_mfma_f32_16x16x32_bf16 v[108:111], v[130:133], v[208:211], v[108:111]
	v_mfma_f32_16x16x32_bf16 v[104:107], v[138:141], v[208:211], v[104:107]
	v_mfma_f32_16x16x32_bf16 v[92:95], v[130:133], v[222:225], v[92:95]
	v_mfma_f32_16x16x32_bf16 v[88:91], v[138:141], v[222:225], v[88:91]
	v_mfma_f32_16x16x32_bf16 v[76:79], v[130:133], v[230:233], v[76:79]
	v_mfma_f32_16x16x32_bf16 v[72:75], v[138:141], v[230:233], v[72:75]
	v_mfma_f32_16x16x32_bf16 v[124:127], v[134:137], v[204:207], v[124:127]
	v_mfma_f32_16x16x32_bf16 v[120:123], v[180:183], v[204:207], v[120:123]
	v_mfma_f32_16x16x32_bf16 v[108:111], v[134:137], v[218:221], v[108:111]
	v_mfma_f32_16x16x32_bf16 v[104:107], v[180:183], v[218:221], v[104:107]
	v_mfma_f32_16x16x32_bf16 v[92:95], v[134:137], v[226:229], v[92:95]
	v_mfma_f32_16x16x32_bf16 v[88:91], v[180:183], v[226:229], v[88:91]
	v_mfma_f32_16x16x32_bf16 v[76:79], v[134:137], v[234:237], v[76:79]
	v_mfma_f32_16x16x32_bf16 v[72:75], v[180:183], v[234:237], v[72:75]
	s_setprio 0
	s_setprio 1
	v_mfma_f32_16x16x32_bf16 v[116:119], v[184:187], v[200:203], v[116:119]
	v_mfma_f32_16x16x32_bf16 v[112:115], v[192:195], v[200:203], v[112:115]
	v_mfma_f32_16x16x32_bf16 v[100:103], v[184:187], v[208:211], v[100:103]
	v_mfma_f32_16x16x32_bf16 v[96:99], v[192:195], v[208:211], v[96:99]
	v_mfma_f32_16x16x32_bf16 v[84:87], v[184:187], v[222:225], v[84:87]
	v_mfma_f32_16x16x32_bf16 v[80:83], v[192:195], v[222:225], v[80:83]
	v_mfma_f32_16x16x32_bf16 v[68:71], v[184:187], v[230:233], v[68:71]
	v_mfma_f32_16x16x32_bf16 v[64:67], v[192:195], v[230:233], v[64:67]
	v_mfma_f32_16x16x32_bf16 v[116:119], v[188:191], v[204:207], v[116:119]
	v_mfma_f32_16x16x32_bf16 v[112:115], v[196:199], v[204:207], v[112:115]
	v_mfma_f32_16x16x32_bf16 v[100:103], v[188:191], v[218:221], v[100:103]
	v_mfma_f32_16x16x32_bf16 v[96:99], v[196:199], v[218:221], v[96:99]
	v_mfma_f32_16x16x32_bf16 v[84:87], v[188:191], v[226:229], v[84:87]
	v_mfma_f32_16x16x32_bf16 v[80:83], v[196:199], v[226:229], v[80:83]
	v_mfma_f32_16x16x32_bf16 v[68:71], v[188:191], v[234:237], v[68:71]
	v_mfma_f32_16x16x32_bf16 v[64:67], v[196:199], v[234:237], v[64:67]
	s_setprio 0
	s_barrier
; #define PG8_STAGE(bufoff, gbase, voff) do { _Pragma("unroll") for (int _i = 0; _i < 2; ++_i) \
;         __builtin_amdgcn_global_load_lds((const unsigned*)((const char*)(gbase) + (voff)[_i]), (LAS unsigned*)(lds + (bufoff) + ldsw + _i * 8192), 16, 0, 0); } while (0)
; #define PG8_LDA(dst, b, h) do { _Pragma("unroll") for (int m = 0; m < 4; ++m) _Pragma("unroll") for (int k = 0; k < 2; ++k) dst[m][k] = *(const LAS bf16x8*)(lds + PG8_SA(b, h) + aoff + m * 2048 + k * 1024); } while (0)
; #define PG8_LDB(dst, b, h) do { _Pragma("unroll") for (int n = 0; n < 2; ++n) _Pragma("unroll") for (int k = 0; k < 2; ++k) dst[n][k] = *(const LAS bf16x8*)(lds + PG8_SB(b, h) + boff + n * 2048 + k * 1024); } while (0)
; #define PG8_MMA(ai, bj, At, Bt) do { __builtin_amdgcn_s_setprio(1); _Pragma("unroll") for (int m = 0; m < 4; ++m) _Pragma("unroll") for (int n = 0; n < 2; ++n) _Pragma("unroll") for (int k = 0; k < 2; ++k) \
;         acc[ai][bj][m][n] = __builtin_amdgcn_mfma_f32_16x16x32_bf16(Bt[n][k], At[m][k], acc[ai][bj][m][n], 0, 0, 0); __builtin_amdgcn_s_setprio(0); } while (0)
; #define PG8_WAIT_V(n) asm volatile("s_waitcnt vmcnt(" #n ")" ::: "memory")
; #define PG8_WAIT_L(n) asm volatile("s_waitcnt lgkmcnt(" #n ")" ::: "memory")
; #define PG8_BAR __builtin_amdgcn_s_barrier()
; #define PG8_SCHED __builtin_amdgcn_sched_barrier(0)
; __device__ __forceinline__ void gemm_phase(LAS unsigned char* lds, const GP p, const int tid) {
;     ...
;             PG8_LDB(B0, 0, 0); PG8_LDB(B1, 0, 1); PG8_SCHED; PG8_LDA(At, 0, 0); PG8_STAGE(PG8_SA(1, 1), a1 + hstep, voffA);
;             PG8_WAIT_V(8); PG8_WAIT_L(0); PG8_BAR; PG8_MMA(0, 0, At, B0); PG8_MMA(0, 1, At, B1); PG8_BAR; PG8_SCHED;
;     ...
;             PG8_LDA(At, 1, 1); PG8_STAGE(PG8_SB(1, 0), b3, voffB); PG8_STAGE(PG8_SB(1, 1), b3 + hstep, voffB); PG8_STAGE(PG8_SA(1, 0), a3, voffA);
;             PG8_WAIT_V(8); PG8_WAIT_L(0); PG8_BAR; PG8_MMA(1, 0, At, B0); PG8_MMA(1, 1, At, B1); PG8_BAR; PG8_SCHED;
	s_add_i32 s43, s43, s52
	v_lshl_add_u64 v[142:143], v[142:143], 0, s[36:37]
	s_mov_b32 m0, s43
	ds_read_b128 v[200:203], v167 offset:49152
	ds_read_b128 v[204:207], v167 offset:50176
	ds_read_b128 v[208:211], v167 offset:51200
	ds_read_b128 v[218:221], v167 offset:52224
	ds_read_b128 v[222:225], v167 offset:53248
	ds_read_b128 v[226:229], v167 offset:54272
	ds_read_b128 v[230:233], v167 offset:55296
	ds_read_b128 v[234:237], v167 offset:56320
	global_load_lds_dwordx4 v[142:143], off
	v_lshl_add_u64 v[142:143], v[238:239], 0, s[36:37]
	s_add_i32 m0, s43, 0x2000
	s_add_i32 s43, s99, s52
	global_load_lds_dwordx4 v[142:143], off
	v_lshl_add_u64 v[142:143], v[240:241], 0, s[36:37]
	s_mov_b32 m0, s43
	s_nop 0
	global_load_lds_dwordx4 v[142:143], off
	v_lshl_add_u64 v[142:143], v[242:243], 0, s[36:37]
	s_add_i32 m0, s43, 0x2000
	s_nop 0
	global_load_lds_dwordx4 v[142:143], off
	v_lshl_add_u64 v[142:143], v[244:245], 0, s[36:37]
	s_mov_b32 m0, s57
	s_nop 0
	global_load_lds_dwordx4 v[142:143], off
	v_lshl_add_u64 v[142:143], v[246:247], 0, s[36:37]
	s_mov_b32 m0, s58
	s_nop 0
	global_load_lds_dwordx4 v[142:143], off
	s_waitcnt vmcnt(8)
	s_waitcnt lgkmcnt(0)
	s_barrier
	s_setprio 1
	s_waitcnt lgkmcnt(0)
	v_mfma_f32_16x16x32_bf16 v[60:63], v[130:133], v[200:203], v[60:63]
	v_mfma_f32_16x16x32_bf16 v[56:59], v[138:141], v[200:203], v[56:59]
	v_mfma_f32_16x16x32_bf16 v[44:47], v[130:133], v[208:211], v[44:47]
	v_mfma_f32_16x16x32_bf16 v[40:43], v[138:141], v[208:211], v[40:43]
	v_mfma_f32_16x16x32_bf16 v[28:31], v[130:133], v[222:225], v[28:31]
	v_mfma_f32_16x16x32_bf16 v[24:27], v[138:141], v[222:225], v[24:27]
	v_mfma_f32_16x16x32_bf16 v[12:15], v[130:133], v[230:233], v[12:15]
	v_mfma_f32_16x16x32_bf16 v[8:11], v[138:141], v[230:233], v[8:11]
	v_mfma_f32_16x16x32_bf16 v[60:63], v[134:137], v[204:207], v[60:63]
	v_mfma_f32_16x16x32_bf16 v[56:59], v[180:183], v[204:207], v[56:59]
	v_mfma_f32_16x16x32_bf16 v[44:47], v[134:137], v[218:221], v[44:47]
	v_mfma_f32_16x16x32_bf16 v[40:43], v[180:183], v[218:221], v[40:43]
	v_mfma_f32_16x16x32_bf16 v[28:31], v[134:137], v[226:229], v[28:31]
	v_mfma_f32_16x16x32_bf16 v[24:27], v[180:183], v[226:229], v[24:27]
	v_mfma_f32_16x16x32_bf16 v[12:15], v[134:137], v[234:237], v[12:15]
	v_mfma_f32_16x16x32_bf16 v[8:11], v[180:183], v[234:237], v[8:11]
	s_setprio 0
	s_setprio 1
	v_mfma_f32_16x16x32_bf16 v[52:55], v[184:187], v[200:203], v[52:55]
	v_mfma_f32_16x16x32_bf16 v[48:51], v[192:195], v[200:203], v[48:51]
	v_mfma_f32_16x16x32_bf16 v[36:39], v[184:187], v[208:211], v[36:39]
	v_mfma_f32_16x16x32_bf16 v[32:35], v[192:195], v[208:211], v[32:35]
	v_mfma_f32_16x16x32_bf16 v[20:23], v[184:187], v[222:225], v[20:23]
	v_mfma_f32_16x16x32_bf16 v[16:19], v[192:195], v[222:225], v[16:19]
	v_mfma_f32_16x16x32_bf16 v[4:7], v[184:187], v[230:233], v[4:7]
	v_mfma_f32_16x16x32_bf16 v[0:3], v[192:195], v[230:233], v[0:3]
	v_mfma_f32_16x16x32_bf16 v[52:55], v[188:191], v[204:207], v[52:55]
	v_mfma_f32_16x16x32_bf16 v[48:51], v[196:199], v[204:207], v[48:51]
	v_mfma_f32_16x16x32_bf16 v[36:39], v[188:191], v[218:221], v[36:39]
	v_mfma_f32_16x16x32_bf16 v[32:35], v[196:199], v[218:221], v[32:35]
	v_mfma_f32_16x16x32_bf16 v[20:23], v[188:191], v[226:229], v[20:23]
	v_mfma_f32_16x16x32_bf16 v[16:19], v[196:199], v[226:229], v[16:19]
	v_mfma_f32_16x16x32_bf16 v[4:7], v[188:191], v[234:237], v[4:7]
	v_mfma_f32_16x16x32_bf16 v[0:3], v[196:199], v[234:237], v[0:3]
	s_setprio 0
	s_barrier
	s_add_u32 s82, s82, 0x100
	s_addc_u32 s83, s83, 0
	s_add_u32 s81, s81, 0x100
	s_addc_u32 s91, s91, 0
	s_cmp_ge_u32 s98, s60
	s_cbranch_scc1 .LBB0_107
	s_branch .LBB0_105
.LBB0_104:
	s_cmp_eq_u32 s98, 0
	s_cbranch_scc1 .Lpeel_body
	s_add_i32 s98, s98, 2
	s_add_u32 s43, s82, 0x80
	s_addc_u32 s99, s83, 0
	s_and_b64 s[86:87], s[84:85], exec
	s_cselect_b32 s87, s77, s99
	s_cselect_b32 s86, s76, s43
	s_add_i32 s43, 0, 0x10000
	s_and_b64 s[84:85], s[84:85], exec
	v_add_u32_e32 v142, s43, v165
	s_cselect_b32 s85, s79, s91
	s_cselect_b32 s84, s78, s81
	s_add_i32 s99, 0, 0x14000
	ds_read_b128 v[130:133], v142
	ds_read_b128 v[134:137], v142 offset:1024
	ds_read_b128 v[138:141], v142 offset:2048
	ds_read_b128 v[180:183], v142 offset:3072
	v_add_u32_e32 v142, s99, v165
	ds_read_b128 v[184:187], v142
	ds_read_b128 v[188:191], v142 offset:1024
	ds_read_b128 v[192:195], v142 offset:2048
	ds_read_b128 v[196:199], v142 offset:3072
	v_lshl_add_u64 v[142:143], s[82:83], 0, v[160:161]
	s_add_i32 m0, s53, 0xc000
	ds_read_b128 v[200:203], v167
	ds_read_b128 v[204:207], v167 offset:1024
	ds_read_b128 v[208:211], v167 offset:2048
	ds_read_b128 v[218:221], v167 offset:3072
	ds_read_b128 v[222:225], v167 offset:4096
	ds_read_b128 v[226:229], v167 offset:5120
	ds_read_b128 v[230:233], v167 offset:6144
	ds_read_b128 v[234:237], v167 offset:7168
	global_load_lds_dwordx4 v[142:143], off
	v_lshl_add_u64 v[142:143], s[82:83], 0, v[162:163]
	s_add_i32 m0, s53, 0xe000
	s_nop 0
	global_load_lds_dwordx4 v[142:143], off
	s_waitcnt vmcnt(8)
	s_waitcnt lgkmcnt(0)
	s_barrier
; #define PG8_STAGE(bufoff, gbase, voff) do { _Pragma("unroll") for (int _i = 0; _i < 2; ++_i) \
;         __builtin_amdgcn_global_load_lds((const unsigned*)((const char*)(gbase) + (voff)[_i]), (LAS unsigned*)(lds + (bufoff) + ldsw + _i * 8192), 16, 0, 0); } while (0)
; #define PG8_LDA(dst, b, h) do { _Pragma("unroll") for (int m = 0; m < 4; ++m) _Pragma("unroll") for (int k = 0; k < 2; ++k) dst[m][k] = *(const LAS bf16x8*)(lds + PG8_SA(b, h) + aoff + m * 2048 + k * 1024); } while (0)
; #define PG8_LDB(dst, b, h) do { _Pragma("unroll") for (int n = 0; n < 2; ++n) _Pragma("unroll") for (int k = 0; k < 2; ++k) dst[n][k] = *(const LAS bf16x8*)(lds + PG8_SB(b, h) + boff + n * 2048 + k * 1024); } while (0)
; #define PG8_MMA(ai, bj, At, Bt) do { __builtin_amdgcn_s_setprio(1); _Pragma("unroll") for (int m = 0; m < 4; ++m) _Pragma("unroll") for (int n = 0; n < 2; ++n) _Pragma("unroll") for (int k = 0; k < 2; ++k) \
;         acc[ai][bj][m][n] = __builtin_amdgcn_mfma_f32_16x16x32_bf16(Bt[n][k], At[m][k], acc[ai][bj][m][n], 0, 0, 0); __builtin_amdgcn_s_setprio(0); } while (0)
; #define PG8_WAIT_V(n) asm volatile("s_waitcnt vmcnt(" #n ")" ::: "memory")
; #define PG8_WAIT_L(n) asm volatile("s_waitcnt lgkmcnt(" #n ")" ::: "memory")
; #define PG8_BAR __builtin_amdgcn_s_barrier()
; #define PG8_SCHED __builtin_amdgcn_sched_barrier(0)
; __device__ __forceinline__ void gemm_phase(LAS unsigned char* lds, const GP p, const int tid) {
;     ...
;             PG8_WAIT_V(8); PG8_WAIT_L(0); PG8_BAR; PG8_MMA(0, 0, At, B0); PG8_MMA(0, 1, At, B1); PG8_BAR; PG8_SCHED;
;             PG8_LDA(At, 0, 1); PG8_STAGE(PG8_SB(0, 0), b2, voffB); PG8_STAGE(PG8_SB(0, 1), b2 + hstep, voffB); PG8_STAGE(PG8_SA(0, 0), a2, voffA);
;             PG8_WAIT_V(8); PG8_WAIT_L(0); PG8_BAR; PG8_MMA(1, 0, At, B0); PG8_MMA(1, 1, At, B1); PG8_BAR; PG8_SCHED;
;             PG8_LDB(B0, 1, 0); PG8_LDB(B1, 1, 1); PG8_SCHED; PG8_LDA(At, 1, 0); PG8_STAGE(PG8_SA(0, 1), a2 + hstep, voffA);
	s_setprio 1
	s_waitcnt lgkmcnt(0)
	v_mfma_f32_16x16x32_bf16 v[124:127], v[130:133], v[200:203], v[124:127]
	v_mfma_f32_16x16x32_bf16 v[120:123], v[138:141], v[200:203], v[120:123]
	v_mfma_f32_16x16x32_bf16 v[108:111], v[130:133], v[208:211], v[108:111]
	v_mfma_f32_16x16x32_bf16 v[104:107], v[138:141], v[208:211], v[104:107]
	v_mfma_f32_16x16x32_bf16 v[92:95], v[130:133], v[222:225], v[92:95]
	v_mfma_f32_16x16x32_bf16 v[88:91], v[138:141], v[222:225], v[88:91]
	v_mfma_f32_16x16x32_bf16 v[76:79], v[130:133], v[230:233], v[76:79]
	v_mfma_f32_16x16x32_bf16 v[72:75], v[138:141], v[230:233], v[72:75]
	v_mfma_f32_16x16x32_bf16 v[124:127], v[134:137], v[204:207], v[124:127]
	v_mfma_f32_16x16x32_bf16 v[120:123], v[180:183], v[204:207], v[120:123]
	v_mfma_f32_16x16x32_bf16 v[108:111], v[134:137], v[218:221], v[108:111]
	v_mfma_f32_16x16x32_bf16 v[104:107], v[180:183], v[218:221], v[104:107]
	v_mfma_f32_16x16x32_bf16 v[92:95], v[134:137], v[226:229], v[92:95]
	v_mfma_f32_16x16x32_bf16 v[88:91], v[180:183], v[226:229], v[88:91]
	v_mfma_f32_16x16x32_bf16 v[76:79], v[134:137], v[234:237], v[76:79]
	v_mfma_f32_16x16x32_bf16 v[72:75], v[180:183], v[234:237], v[72:75]
	s_setprio 0
	s_setprio 1
	v_mfma_f32_16x16x32_bf16 v[116:119], v[184:187], v[200:203], v[116:119]
	v_mfma_f32_16x16x32_bf16 v[112:115], v[192:195], v[200:203], v[112:115]
	v_mfma_f32_16x16x32_bf16 v[100:103], v[184:187], v[208:211], v[100:103]
	v_mfma_f32_16x16x32_bf16 v[96:99], v[192:195], v[208:211], v[96:99]
	v_mfma_f32_16x16x32_bf16 v[84:87], v[184:187], v[222:225], v[84:87]
	v_mfma_f32_16x16x32_bf16 v[80:83], v[192:195], v[222:225], v[80:83]
	v_mfma_f32_16x16x32_bf16 v[68:71], v[184:187], v[230:233], v[68:71]
	v_mfma_f32_16x16x32_bf16 v[64:67], v[192:195], v[230:233], v[64:67]
	v_mfma_f32_16x16x32_bf16 v[116:119], v[188:191], v[204:207], v[116:119]
	v_mfma_f32_16x16x32_bf16 v[112:115], v[196:199], v[204:207], v[112:115]
	v_mfma_f32_16x16x32_bf16 v[100:103], v[188:191], v[218:221], v[100:103]
	v_mfma_f32_16x16x32_bf16 v[96:99], v[196:199], v[218:221], v[96:99]
	v_mfma_f32_16x16x32_bf16 v[84:87], v[188:191], v[226:229], v[84:87]
	v_mfma_f32_16x16x32_bf16 v[80:83], v[196:199], v[226:229], v[80:83]
	v_mfma_f32_16x16x32_bf16 v[68:71], v[188:191], v[234:237], v[68:71]
	v_mfma_f32_16x16x32_bf16 v[64:67], v[196:199], v[234:237], v[64:67]
	s_setprio 0
	s_barrier
	s_add_i32 s43, s43, s52
	v_lshl_add_u64 v[142:143], s[84:85], 0, v[148:149]
	s_mov_b32 m0, s43
	ds_read_b128 v[200:203], v167 offset:16384
	ds_read_b128 v[204:207], v167 offset:17408
	ds_read_b128 v[208:211], v167 offset:18432
	ds_read_b128 v[218:221], v167 offset:19456
	ds_read_b128 v[222:225], v167 offset:20480
	ds_read_b128 v[226:229], v167 offset:21504
	ds_read_b128 v[230:233], v167 offset:22528
	ds_read_b128 v[234:237], v167 offset:23552
	global_load_lds_dwordx4 v[142:143], off
	s_add_i32 m0, s43, 0x2000
	v_lshl_add_u64 v[238:239], s[84:85], 0, v[152:153]
	s_add_u32 s84, s84, s74
	s_addc_u32 s85, s85, 0
	s_add_i32 s43, s99, s52
	global_load_lds_dwordx4 v[238:239], off
	v_lshl_add_u64 v[240:241], s[84:85], 0, v[148:149]
	s_mov_b32 m0, s43
	v_lshl_add_u64 v[242:243], s[84:85], 0, v[152:153]
	global_load_lds_dwordx4 v[240:241], off
	s_add_i32 m0, s43, 0x2000
	v_lshl_add_u64 v[244:245], s[86:87], 0, v[146:147]
	global_load_lds_dwordx4 v[242:243], off
	s_mov_b32 m0, s53
	v_lshl_add_u64 v[246:247], s[86:87], 0, v[150:151]
	global_load_lds_dwordx4 v[244:245], off
	s_mov_b32 m0, s54
	s_nop 0
	global_load_lds_dwordx4 v[246:247], off
	s_waitcnt vmcnt(8)
	s_waitcnt lgkmcnt(0)
	s_barrier
	s_setprio 1
	s_waitcnt lgkmcnt(0)
	v_mfma_f32_16x16x32_bf16 v[60:63], v[130:133], v[200:203], v[60:63]
	v_mfma_f32_16x16x32_bf16 v[56:59], v[138:141], v[200:203], v[56:59]
	v_mfma_f32_16x16x32_bf16 v[44:47], v[130:133], v[208:211], v[44:47]
	v_mfma_f32_16x16x32_bf16 v[40:43], v[138:141], v[208:211], v[40:43]
	v_mfma_f32_16x16x32_bf16 v[28:31], v[130:133], v[222:225], v[28:31]
	v_mfma_f32_16x16x32_bf16 v[24:27], v[138:141], v[222:225], v[24:27]
	v_mfma_f32_16x16x32_bf16 v[12:15], v[130:133], v[230:233], v[12:15]
	v_mfma_f32_16x16x32_bf16 v[8:11], v[138:141], v[230:233], v[8:11]
	v_mfma_f32_16x16x32_bf16 v[60:63], v[134:137], v[204:207], v[60:63]
	v_mfma_f32_16x16x32_bf16 v[56:59], v[180:183], v[204:207], v[56:59]
	v_mfma_f32_16x16x32_bf16 v[44:47], v[134:137], v[218:221], v[44:47]
	v_mfma_f32_16x16x32_bf16 v[40:43], v[180:183], v[218:221], v[40:43]
	v_mfma_f32_16x16x32_bf16 v[28:31], v[134:137], v[226:229], v[28:31]
	v_mfma_f32_16x16x32_bf16 v[24:27], v[180:183], v[226:229], v[24:27]
	v_mfma_f32_16x16x32_bf16 v[12:15], v[134:137], v[234:237], v[12:15]
	v_mfma_f32_16x16x32_bf16 v[8:11], v[180:183], v[234:237], v[8:11]
	s_setprio 0
	s_setprio 1
	v_mfma_f32_16x16x32_bf16 v[52:55], v[184:187], v[200:203], v[52:55]
	v_mfma_f32_16x16x32_bf16 v[48:51], v[192:195], v[200:203], v[48:51]
	v_mfma_f32_16x16x32_bf16 v[36:39], v[184:187], v[208:211], v[36:39]
	v_mfma_f32_16x16x32_bf16 v[32:35], v[192:195], v[208:211], v[32:35]
	v_mfma_f32_16x16x32_bf16 v[20:23], v[184:187], v[222:225], v[20:23]
	v_mfma_f32_16x16x32_bf16 v[16:19], v[192:195], v[222:225], v[16:19]
	v_mfma_f32_16x16x32_bf16 v[4:7], v[184:187], v[230:233], v[4:7]
	v_mfma_f32_16x16x32_bf16 v[0:3], v[192:195], v[230:233], v[0:3]
	v_mfma_f32_16x16x32_bf16 v[52:55], v[188:191], v[204:207], v[52:55]
	v_mfma_f32_16x16x32_bf16 v[48:51], v[196:199], v[204:207], v[48:51]
	v_mfma_f32_16x16x32_bf16 v[36:39], v[188:191], v[218:221], v[36:39]
	v_mfma_f32_16x16x32_bf16 v[32:35], v[196:199], v[218:221], v[32:35]
	v_mfma_f32_16x16x32_bf16 v[20:23], v[188:191], v[226:229], v[20:23]
	v_mfma_f32_16x16x32_bf16 v[16:19], v[196:199], v[226:229], v[16:19]
	v_mfma_f32_16x16x32_bf16 v[4:7], v[188:191], v[234:237], v[4:7]
	v_mfma_f32_16x16x32_bf16 v[0:3], v[196:199], v[234:237], v[0:3]
	s_setprio 0
	s_barrier
; #define PG8_STAGE(bufoff, gbase, voff) do { _Pragma("unroll") for (int _i = 0; _i < 2; ++_i) \
;         __builtin_amdgcn_global_load_lds((const unsigned*)((const char*)(gbase) + (voff)[_i]), (LAS unsigned*)(lds + (bufoff) + ldsw + _i * 8192), 16, 0, 0); } while (0)
; #define PG8_LDA(dst, b, h) do { _Pragma("unroll") for (int m = 0; m < 4; ++m) _Pragma("unroll") for (int k = 0; k < 2; ++k) dst[m][k] = *(const LAS bf16x8*)(lds + PG8_SA(b, h) + aoff + m * 2048 + k * 1024); } while (0)
; #define PG8_LDB(dst, b, h) do { _Pragma("unroll") for (int n = 0; n < 2; ++n) _Pragma("unroll") for (int k = 0; k < 2; ++k) dst[n][k] = *(const LAS bf16x8*)(lds + PG8_SB(b, h) + boff + n * 2048 + k * 1024); } while (0)
; #define PG8_MMA(ai, bj, At, Bt) do { __builtin_amdgcn_s_setprio(1); _Pragma("unroll") for (int m = 0; m < 4; ++m) _Pragma("unroll") for (int n = 0; n < 2; ++n) _Pragma("unroll") for (int k = 0; k < 2; ++k) \
;         acc[ai][bj][m][n] = __builtin_amdgcn_mfma_f32_16x16x32_bf16(Bt[n][k], At[m][k], acc[ai][bj][m][n], 0, 0, 0); __builtin_amdgcn_s_setprio(0); } while (0)
; #define PG8_WAIT_V(n) asm volatile("s_waitcnt vmcnt(" #n ")" ::: "memory")
; #define PG8_WAIT_L(n) asm volatile("s_waitcnt lgkmcnt(" #n ")" ::: "memory")
; #define PG8_BAR __builtin_amdgcn_s_barrier()
; #define PG8_SCHED __builtin_amdgcn_sched_barrier(0)
; __device__ __forceinline__ void gemm_phase(LAS unsigned char* lds, const GP p, const int tid) {
;     ...
;             PG8_LDB(B0, 1, 0); PG8_LDB(B1, 1, 1); PG8_SCHED; PG8_LDA(At, 1, 0); PG8_STAGE(PG8_SA(0, 1), a2 + hstep, voffA);
;             PG8_WAIT_V(8); PG8_WAIT_L(0); PG8_BAR; PG8_MMA(0, 0, At, B0); PG8_MMA(0, 1, At, B1); PG8_BAR; PG8_SCHED;
	s_add_i32 s43, 0, 0x18000
	v_add_u32_e32 v144, s43, v165
	s_add_i32 s99, 0, 0x1c000
	ds_read_b128 v[130:133], v144
	ds_read_b128 v[134:137], v144 offset:1024
	ds_read_b128 v[138:141], v144 offset:2048
	ds_read_b128 v[180:183], v144 offset:3072
	v_add_u32_e32 v144, s99, v165
	ds_read_b128 v[184:187], v144
	ds_read_b128 v[188:191], v144 offset:1024
	ds_read_b128 v[192:195], v144 offset:2048
	ds_read_b128 v[196:199], v144 offset:3072
	s_add_u32 s84, s86, s74
	s_addc_u32 s85, s87, 0
	s_mov_b32 m0, s55
	v_lshl_add_u64 v[248:249], s[84:85], 0, v[146:147]
	ds_read_b128 v[200:203], v167 offset:32768
	ds_read_b128 v[204:207], v167 offset:33792
	ds_read_b128 v[208:211], v167 offset:34816
	ds_read_b128 v[218:221], v167 offset:35840
	ds_read_b128 v[222:225], v167 offset:36864
	ds_read_b128 v[226:229], v167 offset:37888
	ds_read_b128 v[230:233], v167 offset:38912
	ds_read_b128 v[234:237], v167 offset:39936
	global_load_lds_dwordx4 v[248:249], off
	v_lshl_add_u64 v[248:249], s[84:85], 0, v[150:151]
	s_mov_b32 m0, s56
	s_nop 0
	global_load_lds_dwordx4 v[248:249], off
	s_waitcnt vmcnt(8)
	s_waitcnt lgkmcnt(0)
	s_barrier
	s_setprio 1
	s_waitcnt lgkmcnt(0)
	v_mfma_f32_16x16x32_bf16 v[124:127], v[130:133], v[200:203], v[124:127]
	v_mfma_f32_16x16x32_bf16 v[120:123], v[138:141], v[200:203], v[120:123]
	v_mfma_f32_16x16x32_bf16 v[108:111], v[130:133], v[208:211], v[108:111]
	v_mfma_f32_16x16x32_bf16 v[104:107], v[138:141], v[208:211], v[104:107]
	v_mfma_f32_16x16x32_bf16 v[92:95], v[130:133], v[222:225], v[92:95]
	v_mfma_f32_16x16x32_bf16 v[88:91], v[138:141], v[222:225], v[88:91]
	v_mfma_f32_16x16x32_bf16 v[76:79], v[130:133], v[230:233], v[76:79]
	v_mfma_f32_16x16x32_bf16 v[72:75], v[138:141], v[230:233], v[72:75]
	v_mfma_f32_16x16x32_bf16 v[124:127], v[134:137], v[204:207], v[124:127]
	v_mfma_f32_16x16x32_bf16 v[120:123], v[180:183], v[204:207], v[120:123]
	v_mfma_f32_16x16x32_bf16 v[108:111], v[134:137], v[218:221], v[108:111]
	v_mfma_f32_16x16x32_bf16 v[104:107], v[180:183], v[218:221], v[104:107]
	v_mfma_f32_16x16x32_bf16 v[92:95], v[134:137], v[226:229], v[92:95]
	v_mfma_f32_16x16x32_bf16 v[88:91], v[180:183], v[226:229], v[88:91]
	v_mfma_f32_16x16x32_bf16 v[76:79], v[134:137], v[234:237], v[76:79]
	v_mfma_f32_16x16x32_bf16 v[72:75], v[180:183], v[234:237], v[72:75]
	s_setprio 0
	s_setprio 1
	v_mfma_f32_16x16x32_bf16 v[116:119], v[184:187], v[200:203], v[116:119]
	v_mfma_f32_16x16x32_bf16 v[112:115], v[192:195], v[200:203], v[112:115]
	v_mfma_f32_16x16x32_bf16 v[100:103], v[184:187], v[208:211], v[100:103]
	v_mfma_f32_16x16x32_bf16 v[96:99], v[192:195], v[208:211], v[96:99]
	v_mfma_f32_16x16x32_bf16 v[84:87], v[184:187], v[222:225], v[84:87]
	v_mfma_f32_16x16x32_bf16 v[80:83], v[192:195], v[222:225], v[80:83]
	v_mfma_f32_16x16x32_bf16 v[68:71], v[184:187], v[230:233], v[68:71]
	v_mfma_f32_16x16x32_bf16 v[64:67], v[192:195], v[230:233], v[64:67]
	v_mfma_f32_16x16x32_bf16 v[116:119], v[188:191], v[204:207], v[116:119]
	v_mfma_f32_16x16x32_bf16 v[112:115], v[196:199], v[204:207], v[112:115]
	v_mfma_f32_16x16x32_bf16 v[100:103], v[188:191], v[218:221], v[100:103]
	v_mfma_f32_16x16x32_bf16 v[96:99], v[196:199], v[218:221], v[96:99]
	v_mfma_f32_16x16x32_bf16 v[84:87], v[188:191], v[226:229], v[84:87]
	v_mfma_f32_16x16x32_bf16 v[80:83], v[196:199], v[226:229], v[80:83]
	v_mfma_f32_16x16x32_bf16 v[68:71], v[188:191], v[234:237], v[68:71]
	v_mfma_f32_16x16x32_bf16 v[64:67], v[196:199], v[234:237], v[64:67]
	s_setprio 0
	s_barrier
; #define PG8_STAGE(bufoff, gbase, voff) do { _Pragma("unroll") for (int _i = 0; _i < 2; ++_i) \
;         __builtin_amdgcn_global_load_lds((const unsigned*)((const char*)(gbase) + (voff)[_i]), (LAS unsigned*)(lds + (bufoff) + ldsw + _i * 8192), 16, 0, 0); } while (0)
; #define PG8_LDA(dst, b, h) do { _Pragma("unroll") for (int m = 0; m < 4; ++m) _Pragma("unroll") for (int k = 0; k < 2; ++k) dst[m][k] = *(const LAS bf16x8*)(lds + PG8_SA(b, h) + aoff + m * 2048 + k * 1024); } while (0)
; #define PG8_MMA(ai, bj, At, Bt) do { __builtin_amdgcn_s_setprio(1); _Pragma("unroll") for (int m = 0; m < 4; ++m) _Pragma("unroll") for (int n = 0; n < 2; ++n) _Pragma("unroll") for (int k = 0; k < 2; ++k) \
;         acc[ai][bj][m][n] = __builtin_amdgcn_mfma_f32_16x16x32_bf16(Bt[n][k], At[m][k], acc[ai][bj][m][n], 0, 0, 0); __builtin_amdgcn_s_setprio(0); } while (0)
; #define PG8_WAIT_V(n) asm volatile("s_waitcnt vmcnt(" #n ")" ::: "memory")
; #define PG8_WAIT_L(n) asm volatile("s_waitcnt lgkmcnt(" #n ")" ::: "memory")
; #define PG8_BAR __builtin_amdgcn_s_barrier()
; #define PG8_SCHED __builtin_amdgcn_sched_barrier(0)
; __device__ __forceinline__ void gemm_phase(LAS unsigned char* lds, const GP p, const int tid) {
;     ...
;             PG8_LDA(At, 1, 1); PG8_STAGE(PG8_SB(1, 0), b3, voffB); PG8_STAGE(PG8_SB(1, 1), b3 + hstep, voffB); PG8_STAGE(PG8_SA(1, 0), a3, voffA);
;             PG8_WAIT_V(8); PG8_WAIT_L(0); PG8_BAR; PG8_MMA(1, 0, At, B0); PG8_MMA(1, 1, At, B1); PG8_BAR; PG8_SCHED;
	s_add_i32 s43, s43, s52
	v_lshl_add_u64 v[142:143], v[142:143], 0, s[36:37]
	s_mov_b32 m0, s43
	ds_read_b128 v[200:203], v167 offset:49152
	ds_read_b128 v[204:207], v167 offset:50176
	ds_read_b128 v[208:211], v167 offset:51200
	ds_read_b128 v[218:221], v167 offset:52224
	ds_read_b128 v[222:225], v167 offset:53248
	ds_read_b128 v[226:229], v167 offset:54272
	ds_read_b128 v[230:233], v167 offset:55296
	ds_read_b128 v[234:237], v167 offset:56320
	global_load_lds_dwordx4 v[142:143], off
	v_lshl_add_u64 v[142:143], v[238:239], 0, s[36:37]
	s_add_i32 m0, s43, 0x2000
	s_add_i32 s43, s99, s52
	global_load_lds_dwordx4 v[142:143], off
	v_lshl_add_u64 v[142:143], v[240:241], 0, s[36:37]
	s_mov_b32 m0, s43
	s_nop 0
	global_load_lds_dwordx4 v[142:143], off
	v_lshl_add_u64 v[142:143], v[242:243], 0, s[36:37]
	s_add_i32 m0, s43, 0x2000
	s_nop 0
	global_load_lds_dwordx4 v[142:143], off
	v_lshl_add_u64 v[142:143], v[244:245], 0, s[36:37]
	s_mov_b32 m0, s57
	s_nop 0
	global_load_lds_dwordx4 v[142:143], off
	v_lshl_add_u64 v[142:143], v[246:247], 0, s[36:37]
	s_mov_b32 m0, s58
	s_nop 0
	global_load_lds_dwordx4 v[142:143], off
	s_waitcnt vmcnt(8)
	s_waitcnt lgkmcnt(0)
	s_barrier
	s_setprio 1
	s_waitcnt lgkmcnt(0)
	v_mfma_f32_16x16x32_bf16 v[60:63], v[130:133], v[200:203], v[60:63]
	v_mfma_f32_16x16x32_bf16 v[56:59], v[138:141], v[200:203], v[56:59]
	v_mfma_f32_16x16x32_bf16 v[44:47], v[130:133], v[208:211], v[44:47]
	v_mfma_f32_16x16x32_bf16 v[40:43], v[138:141], v[208:211], v[40:43]
	v_mfma_f32_16x16x32_bf16 v[28:31], v[130:133], v[222:225], v[28:31]
	v_mfma_f32_16x16x32_bf16 v[24:27], v[138:141], v[222:225], v[24:27]
	v_mfma_f32_16x16x32_bf16 v[12:15], v[130:133], v[230:233], v[12:15]
	v_mfma_f32_16x16x32_bf16 v[8:11], v[138:141], v[230:233], v[8:11]
	v_mfma_f32_16x16x32_bf16 v[60:63], v[134:137], v[204:207], v[60:63]
	v_mfma_f32_16x16x32_bf16 v[56:59], v[180:183], v[204:207], v[56:59]
	v_mfma_f32_16x16x32_bf16 v[44:47], v[134:137], v[218:221], v[44:47]
	v_mfma_f32_16x16x32_bf16 v[40:43], v[180:183], v[218:221], v[40:43]
	v_mfma_f32_16x16x32_bf16 v[28:31], v[134:137], v[226:229], v[28:31]
	v_mfma_f32_16x16x32_bf16 v[24:27], v[180:183], v[226:229], v[24:27]
	v_mfma_f32_16x16x32_bf16 v[12:15], v[134:137], v[234:237], v[12:15]
	v_mfma_f32_16x16x32_bf16 v[8:11], v[180:183], v[234:237], v[8:11]
	s_setprio 0
	s_setprio 1
	v_mfma_f32_16x16x32_bf16 v[52:55], v[184:187], v[200:203], v[52:55]
	v_mfma_f32_16x16x32_bf16 v[48:51], v[192:195], v[200:203], v[48:51]
	v_mfma_f32_16x16x32_bf16 v[36:39], v[184:187], v[208:211], v[36:39]
	v_mfma_f32_16x16x32_bf16 v[32:35], v[192:195], v[208:211], v[32:35]
	v_mfma_f32_16x16x32_bf16 v[20:23], v[184:187], v[222:225], v[20:23]
	v_mfma_f32_16x16x32_bf16 v[16:19], v[192:195], v[222:225], v[16:19]
	v_mfma_f32_16x16x32_bf16 v[4:7], v[184:187], v[230:233], v[4:7]
	v_mfma_f32_16x16x32_bf16 v[0:3], v[192:195], v[230:233], v[0:3]
	v_mfma_f32_16x16x32_bf16 v[52:55], v[188:191], v[204:207], v[52:55]
	v_mfma_f32_16x16x32_bf16 v[48:51], v[196:199], v[204:207], v[48:51]
	v_mfma_f32_16x16x32_bf16 v[36:39], v[188:191], v[218:221], v[36:39]
	v_mfma_f32_16x16x32_bf16 v[32:35], v[196:199], v[218:221], v[32:35]
	v_mfma_f32_16x16x32_bf16 v[20:23], v[188:191], v[226:229], v[20:23]
	v_mfma_f32_16x16x32_bf16 v[16:19], v[196:199], v[226:229], v[16:19]
	v_mfma_f32_16x16x32_bf16 v[4:7], v[188:191], v[234:237], v[4:7]
	v_mfma_f32_16x16x32_bf16 v[0:3], v[196:199], v[234:237], v[0:3]
	s_setprio 0
	s_barrier
	s_add_u32 s82, s82, 0x100
	s_addc_u32 s83, s83, 0
	s_add_u32 s81, s81, 0x100
	s_addc_u32 s91, s91, 0
	s_cmp_ge_u32 s98, s60
	s_cbranch_scc1 .LBB0_107
